# tail share 128 of 512 HG_IN row blocks on the GEMM half
# baseline (speedup 1.0000x reference)
; __device__ __forceinline__ void p0_split_tail(Frame& F, int my, int nconv) {
;     const int gw0 = F.gw, ngw0 = F.ngw; F.gw = my * NWAVES + F.wave; F.ngw = nconv * NWAVES;
;     int it0 = 0;
;     p0_transpose_matrix2(F, FIN(F, 15), DM, HG_NP, (bf16*)FW(F, WS_W_HG_IN), HG_NP / 32 - P_HG_SPLIT, [](int nb) { return (P_HG_SPLIT + nb) * 32; }, [](int nb) { return (P_HG_SPLIT + nb) * 32; }, it0, FIN(F, 1) + 2 * DM);
;     F.gw = gw0; F.ngw = ngw0;
; }
.LBB0_260:
	v_readlane_b32 s4, v254, 7
	v_readlane_b32 s5, v254, 8
	s_waitcnt vmcnt(0)
	s_barrier
	s_barrier
	v_readlane_b32 s62, v254, 7
	v_readlane_b32 s63, v254, 8
	s_nop 3
	s_load_dwordx2 s[44:45], s[62:63], 0x78
	s_load_dwordx2 s[52:53], s[62:63], 0x8
	s_waitcnt lgkmcnt(0)
	s_add_u32 s52, s52, 0x8000
	s_addc_u32 s53, s53, 0
	s_mov_b32 s46, 0x10000
	s_mov_b32 s47, 0
	s_add_u32 s48, s70, 0x15600000
	s_addc_u32 s49, s71, 0
	s_mov_b32 s50, 32
	s_mov_b32 s51, 0x20
	s_mov_b32 s54, 384
	s_mov_b32 s55, 0
	s_lshl_b32 s56, s33, 3
	s_add_i32 s56, s56, s90
	s_mov_b32 s32, 0
	s_branch .Lcva_run

; __device__ __forceinline__ void p0_split_convert(Frame& F, int my, int nconv, unsigned* flag) {
;     ...
;     p0_transpose_matrix(F, FIN(F, 15), DM, HG_NP, (bf16*)FW(F, WS_W_HG_IN), P_HG_SPLIT, [](int nb) { return nb * 32; }, it0, FIN(F, 1) + 2 * DM);
.Lcv_ret3:
	v_readlane_b32 s62, v254, 7
	v_readlane_b32 s63, v254, 8
	s_nop 3
	s_load_dwordx2 s[44:45], s[62:63], 0x78
	s_load_dwordx2 s[52:53], s[62:63], 0x8
	s_waitcnt lgkmcnt(0)
	s_add_u32 s52, s52, 0x8000
	s_addc_u32 s53, s53, 0
	s_mov_b32 s46, 0x10000
	s_mov_b32 s47, 0
	s_add_u32 s48, s70, 0x15600000
	s_addc_u32 s49, s71, 0
	s_mov_b32 s50, 96
	s_mov_b32 s51, 0x40000a
	s_mov_b32 s54, 0
	s_mov_b32 s55, 640
	s_mov_b32 s56, s19
	s_mov_b32 s32, 4
	s_branch .Lcva_run
